# P3 delta items segment (c): B fragments of k-steps 1..3 read together (counted lgkmcnt) on top of the hoisted decay reads
# baseline (speedup 1.0000x reference)
.LBB0_333:
	s_waitcnt lgkmcnt(0)
	s_barrier
	ds_read2st64_b32 v[10:11], v147 offset0:136 offset1:138
	v_add_u32_e32 v18, 64, v147
	ds_read2st64_b32 v[12:13], v18 offset0:136 offset1:138
	v_add_u32_e32 v19, 0x80, v147
	ds_read2st64_b32 v[14:15], v19 offset0:136 offset1:138
	v_add_u32_e32 v18, 0xc0, v147
	ds_read2st64_b32 v[16:17], v18 offset0:136 offset1:138
	ds_read_b128 v[2:5], v148 offset:34816
	ds_read_b128 v[6:9], v148 offset:35328
	ds_read_b128 v[34:37], v213
	ds_read_b128 v[38:41], v213 offset:17408
	ds_read_b128 v[42:45], v214
	ds_read_b128 v[50:53], v214 offset:4352
	ds_read_b128 v[58:61], v214 offset:8704
	ds_read_b128 v[66:69], v214 offset:13056
	s_waitcnt lgkmcnt(3)
	v_mfma_f32_16x16x32_bf16 v[46:49], v[34:37], v[42:45], 0
	v_readlane_b32 s2, v250, 14
	v_readlane_b32 s3, v250, 15
	v_mfma_f32_16x16x32_bf16 v[42:45], v[38:41], v[42:45], 0
	s_waitcnt lgkmcnt(2)
	v_mfma_f32_16x16x32_bf16 v[54:57], v[34:37], v[50:53], 0
	v_mfma_f32_16x16x32_bf16 v[50:53], v[38:41], v[50:53], 0
	s_waitcnt lgkmcnt(1)
	v_mfma_f32_16x16x32_bf16 v[62:65], v[34:37], v[58:61], 0
	v_mfma_f32_16x16x32_bf16 v[58:61], v[38:41], v[58:61], 0
	s_waitcnt lgkmcnt(0)
	v_mfma_f32_16x16x32_bf16 v[34:37], v[34:37], v[66:69], 0
	v_mfma_f32_16x16x32_bf16 v[38:41], v[38:41], v[66:69], 0
	ds_read_b128 v[66:69], v213 offset:64
	ds_read_b128 v[96:99], v213 offset:17472
	ds_read_b128 v[100:103], v214 offset:64
	ds_read_b128 v[18:21], v214 offset:4416
	ds_read_b128 v[22:25], v214 offset:8768
	ds_read_b128 v[26:29], v214 offset:13120
	s_waitcnt lgkmcnt(3)
	v_mfma_f32_16x16x32_bf16 v[46:49], v[66:69], v[100:103], v[46:49]
	v_mfma_f32_16x16x32_bf16 v[42:45], v[96:99], v[100:103], v[42:45]
	s_waitcnt lgkmcnt(2)
	v_mfma_f32_16x16x32_bf16 v[54:57], v[66:69], v[18:21], v[54:57]
	v_mfma_f32_16x16x32_bf16 v[50:53], v[96:99], v[18:21], v[50:53]
	s_waitcnt lgkmcnt(1)
	v_mfma_f32_16x16x32_bf16 v[62:65], v[66:69], v[22:25], v[62:65]
	v_mfma_f32_16x16x32_bf16 v[58:61], v[96:99], v[22:25], v[58:61]
	s_waitcnt lgkmcnt(0)
	v_mfma_f32_16x16x32_bf16 v[34:37], v[66:69], v[26:29], v[34:37]
	v_mfma_f32_16x16x32_bf16 v[38:41], v[96:99], v[26:29], v[38:41]
	ds_read_b128 v[66:69], v213 offset:128
	ds_read_b128 v[96:99], v213 offset:17536
	ds_read_b128 v[100:103], v214 offset:128
	ds_read_b128 v[18:21], v214 offset:4480
	ds_read_b128 v[22:25], v214 offset:8832
	ds_read_b128 v[26:29], v214 offset:13184
	s_waitcnt lgkmcnt(3)
	v_mfma_f32_16x16x32_bf16 v[46:49], v[66:69], v[100:103], v[46:49]
	v_mfma_f32_16x16x32_bf16 v[42:45], v[96:99], v[100:103], v[42:45]
	s_waitcnt lgkmcnt(2)
	v_mfma_f32_16x16x32_bf16 v[54:57], v[66:69], v[18:21], v[54:57]
	v_mfma_f32_16x16x32_bf16 v[50:53], v[96:99], v[18:21], v[50:53]
	s_waitcnt lgkmcnt(1)
	v_mfma_f32_16x16x32_bf16 v[104:107], v[66:69], v[22:25], v[62:65]
	v_mfma_f32_16x16x32_bf16 v[100:103], v[96:99], v[22:25], v[58:61]
	s_nop 2
	s_waitcnt lgkmcnt(0)
	v_mfma_f32_16x16x32_bf16 v[34:37], v[66:69], v[26:29], v[34:37]
	v_mfma_f32_16x16x32_bf16 v[66:69], v[96:99], v[26:29], v[38:41]
	s_nop 2
	ds_read_b128 v[38:41], v213 offset:192
	ds_read_b128 v[96:99], v213 offset:17600
	ds_read_b128 v[58:61], v214 offset:192
	ds_read_b128 v[18:21], v214 offset:4544
	ds_read_b128 v[22:25], v214 offset:8896
	ds_read_b128 v[26:29], v214 offset:13248
	s_waitcnt lgkmcnt(3)
	v_mfma_f32_16x16x32_bf16 v[62:65], v[38:41], v[58:61], v[46:49]
	v_mfma_f32_16x16x32_bf16 v[58:61], v[96:99], v[58:61], v[42:45]
	s_nop 2
	s_waitcnt lgkmcnt(2)
	v_mfma_f32_16x16x32_bf16 v[54:57], v[38:41], v[18:21], v[54:57]
	v_mfma_f32_16x16x32_bf16 v[50:53], v[96:99], v[18:21], v[50:53]
	s_waitcnt lgkmcnt(1)
	v_mfma_f32_16x16x32_bf16 v[46:49], v[38:41], v[22:25], v[104:107]
	v_mfma_f32_16x16x32_bf16 v[42:45], v[96:99], v[22:25], v[100:103]
	s_nop 2
	s_waitcnt lgkmcnt(0)
	v_mfma_f32_16x16x32_bf16 v[38:41], v[38:41], v[26:29], v[34:37]
	v_mfma_f32_16x16x32_bf16 v[34:37], v[96:99], v[26:29], v[66:69]
	v_mov_b32_e32 v96, v10
	v_mov_b32_e32 v97, v11
	s_nop 1
	v_mov_b32_e32 v66, v2
	v_cndmask_b32_e64 v68, 0, 1, s[2:3]
	v_cmp_ne_u32_e64 s[68:69], 1, v68
	s_waitcnt lgkmcnt(0)
	v_sub_f32_e32 v66, v66, v96
	v_mul_f32_e64 v66, |v66|, s51
	v_exp_f32_e32 v67, v66
	v_mov_b32_e32 v66, 0
	s_and_saveexec_b64 s[2:3], s[4:5]
	s_cbranch_execz .LBB0_337
	s_and_b64 vcc, exec, s[68:69]
	v_mov_b32_e32 v66, v97
	s_cbranch_vccnz .LBB0_336
	v_mov_b32_e32 v66, v6
